# gemm_in: tile's four row sum-of-squares loads issued at the tile prologue instead of in the last K step
# speedup vs baseline: 1.0070x; 1.0036x over previous
; DI int tid_() { int t = threadIdx.x; asm volatile("" : "+v"(t)); return t; }
; #define LASP __attribute__((address_space(3)))
; DI void gemm_dma(f32x4 (&acc)[4][4], const bf16_t* Ap, int lda, const bf16_t* Bp, int ldb, int K, char* lds) {
;   const int tid = tid_(), wave = __builtin_amdgcn_readfirstlane(tid >> 6), lane = tid & 63;
;   const int wm = wave >> 1, wn = wave & 1, l15 = lane & 15, quad = lane >> 4;
;   const int nk = K / 64;
;   const int lrow = lane >> 3, lpc = lane & 7;
;   const bf16_t* ga[4]; const bf16_t* gb[4];
; #pragma unroll
;   for (int i = 0; i < 4; ++i) {
;     const int row = (wave * 4 + i) * 8 + lrow; const int q = lpc ^ (row & 7);
;     ga[i] = Ap + (size_t)row * lda + q * 8; gb[i] = Bp + (size_t)row * ldb + q * 8;
;   }
;   auto issue = [&](int kt) {
;     char* sb = lds + (kt & 1) * 32768 + wave * 4096;
; #pragma unroll
;     for (int i = 0; i < 4; ++i) {
;       __builtin_amdgcn_global_load_lds((const unsigned*)(ga[i] + kt * 64), (LASP unsigned*)(sb + i * 1024), 16, 0, 0);
;       __builtin_amdgcn_global_load_lds((const unsigned*)(gb[i] + kt * 64), (LASP unsigned*)(sb + 16384 + i * 1024), 16, 0, 0);
;     }
;   };
;   const int sw = l15 & 7;
;   const unsigned lbase = (unsigned)(size_t)(LASP char*)lds;
;   const unsigned a0 = (unsigned)((wm * 64 + l15) * 128 + ((quad ^ sw) * 16)), a1 = (unsigned)((wm * 64 + l15) * 128 + (((4 + quad) ^ sw) * 16));
;   const unsigned b0 = 16384u + (unsigned)((wn * 64 + l15) * 128 + ((quad ^ sw) * 16)), b1 = 16384u + (unsigned)((wn * 64 + l15) * 128 + (((4 + quad) ^ sw) * 16));
;   asm volatile("s_waitcnt vmcnt(0)" ::: "memory");
;   __builtin_amdgcn_s_barrier();
;   asm volatile("" ::: "memory");
;   issue(0);
; DI void phase_gemm_in(const Params& p, int l, char* lds) {
;   const int tid = tid_(), wave = __builtin_amdgcn_readfirstlane(tid >> 6), lane = tid & 63;
;   const int wm = wave >> 1, wn = wave & 1, l15 = lane & 15, quad = lane >> 4;
;   const bf16_t* Wt = p.wt_in;
;   const int NTN = 49, NTM = 132;
;   for (int r = 0;; ++r) {
;     const int g = xcd_tile(r, NTN * NTM); if (g < 0) break;
;     int mt, nt; tile_decode(g, NTM, NTN, mt, nt);
;     f32x4 acc[4][4]; zero_acc(acc);
;     gemm_dma(acc, p.hn + (size_t)mt * 128 * DM, DM, Wt + (size_t)nt * 128 * DM, DM, DM, lds);
.LBB0_68:
	s_mul_hi_u32 s0, s20, 0x5397829d
	s_lshr_b32 s21, s0, 7
	s_lshl_b32 s0, s21, 3
	s_sub_i32 s1, 0x84, s0
	s_min_i32 s1, s1, 8
	s_abs_i32 s2, s1
	v_cvt_f32_u32_e32 v0, s2
	s_sub_i32 s24, 0, s2
	s_mul_i32 s3, s21, 0xfffffe78
	s_add_i32 s3, s3, s20
	v_rcp_iflag_f32_e32 v0, v0
	s_abs_i32 s22, s3
	s_xor_b32 s23, s3, s1
	s_ashr_i32 s23, s23, 31
	v_mul_f32_e32 v0, 0x4f7ffffe, v0
	v_cvt_u32_f32_e32 v0, v0
	v_readlane_b32 s68, v251, 49
	v_readlane_b32 s72, v251, 53
	v_mov_b32_e32 v26, v212
	v_readfirstlane_b32 s25, v0
	s_mul_i32 s24, s24, s25
	s_mul_hi_u32 s24, s25, s24
	s_add_i32 s25, s25, s24
	s_mul_hi_u32 s24, s22, s25
	s_mul_i32 s25, s24, s2
	s_sub_i32 s22, s22, s25
	s_add_i32 s26, s24, 1
	s_sub_i32 s25, s22, s2
	s_cmp_ge_u32 s22, s2
	s_cselect_b32 s24, s26, s24
	s_cselect_b32 s22, s25, s22
	s_add_i32 s25, s24, 1
	s_cmp_ge_u32 s22, s2
	s_cselect_b32 s2, s25, s24
	s_add_i32 s3, s3, s0
	s_xor_b32 s0, s2, s23
	s_sub_i32 s0, s0, s23
	s_mul_i32 s30, s0, s1
	s_sub_i32 s2, s3, s30
	s_ashr_i32 s3, s2, 31
	s_lshl_b64 s[22:23], s[2:3], 18
	s_add_u32 s24, s8, s22
	s_addc_u32 s25, s9, s23
	s_ashr_i32 s1, s0, 31
	s_lshl_b64 s[22:23], s[0:1], 18
	v_readlane_b32 s73, v251, 54
	s_add_u32 s26, s72, s22
	s_addc_u32 s27, s73, s23
	v_readfirstlane_b32 s1, v26
	s_ashr_i32 s3, s1, 6
	v_bfe_u32 v0, v26, 3, 3
	s_waitcnt lgkmcnt(0)
	v_lshl_or_b32 v2, s3, 5, v0
	v_bitop3_b32 v0, v0, v26, 7 bitop3:0x78
	v_bfe_u32 v27, v26, 4, 2
	v_and_b32_e32 v28, 7, v26
	v_lshlrev_b32_e32 v0, 4, v0
	v_ashrrev_i32_e32 v3, 31, v2
	v_and_b32_e32 v29, 15, v26
	v_lshl_add_u64 v[4:5], s[24:25], 0, v[0:1]
	v_lshlrev_b64 v[8:9], 11, v[2:3]
	v_or_b32_e32 v14, 8, v2
	s_lshr_b32 s24, s1, 1
	v_bitop3_b32 v26, v27, v26, 7 bitop3:0x78
	v_bitop3_b32 v27, v27, v28, 4 bitop3:0x36
	v_and_or_b32 v28, s1, 64, v29
	s_lshl_b32 s1, s3, 12
	v_lshl_add_u64 v[6:7], s[26:27], 0, v[0:1]
	v_lshl_add_u64 v[10:11], v[4:5], 0, v[8:9]
	v_ashrrev_i32_e32 v15, 31, v14
	s_nop 0
	s_barrier
	s_lshl_b32 s46, s2, 7
	v_readlane_b32 s68, v254, 52
	v_readlane_b32 s69, v254, 53
	v_add_u32_e32 v226, s46, v71
	v_ashrrev_i32_e32 v227, 31, v226
	v_lshl_add_u64 v[226:227], v[226:227], 2, s[68:69]
	global_load_dword v222, v[226:227], off
	global_load_dword v223, v[226:227], off offset:64
	global_load_dword v224, v[226:227], off offset:128
	global_load_dword v225, v[226:227], off offset:192
	s_add_i32 s3, s1, 0x4000
	s_mov_b32 m0, s1
	v_lshl_add_u64 v[12:13], v[6:7], 0, v[8:9]
	v_lshlrev_b64 v[14:15], 11, v[14:15]
	v_or_b32_e32 v20, 16, v2
	global_load_lds_dwordx4 v[10:11], off
	s_mov_b32 m0, s3
	v_lshl_add_u64 v[16:17], v[4:5], 0, v[14:15]
	v_ashrrev_i32_e32 v21, 31, v20
	global_load_lds_dwordx4 v[12:13], off
	s_or_b32 m0, s1, 0x400
	v_lshl_add_u64 v[18:19], v[6:7], 0, v[14:15]
	v_lshlrev_b64 v[20:21], 11, v[20:21]
	v_or_b32_e32 v2, 24, v2
	global_load_lds_dwordx4 v[16:17], off
	s_add_i32 m0, s1, 0x4400
	v_lshl_add_u64 v[22:23], v[4:5], 0, v[20:21]
	v_ashrrev_i32_e32 v3, 31, v2
	global_load_lds_dwordx4 v[18:19], off
	s_or_b32 m0, s1, 0x800
	v_lshl_add_u64 v[24:25], v[6:7], 0, v[20:21]
	v_lshlrev_b64 v[2:3], 11, v[2:3]
	global_load_lds_dwordx4 v[22:23], off
	s_add_i32 m0, s1, 0x4800
	v_lshl_add_u64 v[4:5], v[4:5], 0, v[2:3]
	global_load_lds_dwordx4 v[24:25], off
	s_or_b32 m0, s1, 0xc00
	v_lshl_add_u64 v[6:7], v[6:7], 0, v[2:3]
	global_load_lds_dwordx4 v[4:5], off
	s_add_i32 m0, s1, 0x4c00
	s_sub_i32 s3, s20, s30
	global_load_lds_dwordx4 v[6:7], off
	s_mulk_i32 s21, 0x180
	s_sub_i32 s20, s3, s21
	s_ashr_i32 s21, s20, 31
	s_and_b32 s24, s24, 0x1ffffc0
	s_lshl_b64 s[20:21], s[20:21], 18
	v_or_b32_e32 v30, s24, v29
	v_lshl_add_u64 v[4:5], s[20:21], 0, v[8:9]
	v_readlane_b32 s24, v254, 19
	v_or_b32_e32 v4, v4, v0
	v_readlane_b32 s25, v254, 20
	v_readlane_b32 s26, v254, 21
	v_readlane_b32 s27, v254, 22
	v_lshl_add_u64 v[66:67], s[24:25], 0, v[4:5]
	v_lshl_add_u64 v[4:5], s[22:23], 0, v[8:9]
	v_or_b32_e32 v4, v4, v0
	v_lshl_add_u64 v[68:69], s[26:27], 0, v[4:5]
	v_lshl_add_u64 v[4:5], s[20:21], 0, v[14:15]
	v_or_b32_e32 v4, v4, v0
	v_lshl_add_u64 v[74:75], s[24:25], 0, v[4:5]
	v_lshl_add_u64 v[4:5], s[22:23], 0, v[14:15]
	v_or_b32_e32 v4, v4, v0
	v_lshl_add_u64 v[76:77], s[26:27], 0, v[4:5]
	v_lshl_add_u64 v[4:5], s[20:21], 0, v[20:21]
	v_or_b32_e32 v4, v4, v0
	v_lshl_add_u64 v[78:79], s[24:25], 0, v[4:5]
	v_lshl_add_u64 v[4:5], s[22:23], 0, v[20:21]
	v_or_b32_e32 v4, v4, v0
	v_lshl_add_u64 v[80:81], s[26:27], 0, v[4:5]
	v_lshl_add_u64 v[4:5], s[20:21], 0, v[2:3]
	v_lshl_add_u64 v[2:3], s[22:23], 0, v[2:3]
	v_lshlrev_b32_e32 v30, 7, v30
	v_lshlrev_b32_e32 v26, 4, v26
	v_lshlrev_b32_e32 v27, 4, v27
	v_lshlrev_b32_e32 v28, 7, v28
	v_or_b32_e32 v4, v4, v0
	v_or_b32_e32 v2, v2, v0
	v_mov_b32_e32 v50, 0
	v_or_b32_e32 v86, v30, v26
	v_or_b32_e32 v87, v30, v27
	v_or3_b32 v89, v28, v26, s91
	v_or3_b32 v88, v28, v27, s91
	v_lshl_add_u64 v[82:83], s[24:25], 0, v[4:5]
	v_lshl_add_u64 v[84:85], s[26:27], 0, v[2:3]
	s_mov_b64 s[22:23], 0
	s_mov_b32 s3, 0
	v_mov_b32_e32 v51, v50
	v_mov_b32_e32 v52, v50
	v_mov_b32_e32 v53, v50
	v_mov_b32_e32 v2, v50
	v_mov_b32_e32 v3, v50
	v_mov_b32_e32 v4, v50
	v_mov_b32_e32 v5, v50
	v_mov_b32_e32 v6, v50
	v_mov_b32_e32 v7, v50
	v_mov_b32_e32 v8, v50
	v_mov_b32_e32 v9, v50
	v_mov_b32_e32 v10, v50
	v_mov_b32_e32 v11, v50
	v_mov_b32_e32 v12, v50
	v_mov_b32_e32 v13, v50
	v_mov_b32_e32 v14, v50
	v_mov_b32_e32 v15, v50
	v_mov_b32_e32 v16, v50
	v_mov_b32_e32 v17, v50
	v_mov_b32_e32 v18, v50
	v_mov_b32_e32 v19, v50
	v_mov_b32_e32 v20, v50
	v_mov_b32_e32 v21, v50
	v_mov_b32_e32 v22, v50
	v_mov_b32_e32 v23, v50
	v_mov_b32_e32 v24, v50
	v_mov_b32_e32 v25, v50
	v_mov_b32_e32 v26, v50
	v_mov_b32_e32 v27, v50
	v_mov_b32_e32 v28, v50
	v_mov_b32_e32 v29, v50
	v_mov_b32_e32 v30, v50
	v_mov_b32_e32 v31, v50
	v_mov_b32_e32 v32, v50
	v_mov_b32_e32 v33, v50
	v_mov_b32_e32 v34, v50
	v_mov_b32_e32 v35, v50
	v_mov_b32_e32 v36, v50
	v_mov_b32_e32 v37, v50
	v_mov_b32_e32 v38, v50
	v_mov_b32_e32 v39, v50
	v_mov_b32_e32 v40, v50
	v_mov_b32_e32 v41, v50
	v_mov_b32_e32 v42, v50
	v_mov_b32_e32 v43, v50
	v_mov_b32_e32 v44, v50
	v_mov_b32_e32 v45, v50
	v_mov_b32_e32 v46, v50
	v_mov_b32_e32 v47, v50
	v_mov_b32_e32 v48, v50
	v_mov_b32_e32 v49, v50
	v_mov_b32_e32 v54, v50
	v_mov_b32_e32 v55, v50
	v_mov_b32_e32 v56, v50
	v_mov_b32_e32 v57, v50
	v_mov_b32_e32 v58, v50
	v_mov_b32_e32 v59, v50
	v_mov_b32_e32 v60, v50
	v_mov_b32_e32 v61, v50
	v_mov_b32_e32 v62, v50
	v_mov_b32_e32 v63, v50
	v_mov_b32_e32 v64, v50
	v_mov_b32_e32 v65, v50
	v_readlane_b32 s69, v251, 50
	v_readlane_b32 s70, v251, 51
	v_readlane_b32 s71, v251, 52
	v_readlane_b32 s74, v251, 55
	v_readlane_b32 s75, v251, 56
	v_readlane_b32 s76, v251, 57
	v_readlane_b32 s77, v251, 58
	v_readlane_b32 s78, v251, 59
	v_readlane_b32 s79, v251, 60
	v_readlane_b32 s80, v251, 61
	v_readlane_b32 s81, v251, 62
	v_readlane_b32 s82, v251, 63
	v_readlane_b32 s83, v252, 0
; DI void gemm_dma(f32x4 (&acc)[4][4], const bf16_t* Ap, int lda, const bf16_t* Bp, int ldb, int K, char* lds) {
;     ...
;   for (int kt = 0; kt < nk; ++kt) {
;     asm volatile("s_waitcnt vmcnt(0)" ::: "memory");
;     __builtin_amdgcn_s_barrier();
;     asm volatile("" ::: "memory");
;     if (kt + 1 < nk) issue(kt + 1);
;     const unsigned sa = lbase + (unsigned)((kt & 1) * 32768);
;     bf16x8 af[4], bfr[4], ag[4], bg[4];
;     asm volatile("ds_read_b128 %0, %8\n\tds_read_b128 %1, %8 offset:2048\n\tds_read_b128 %2, %8 offset:4096\n\tds_read_b128 %3, %8 offset:6144\n\t"
;                  "ds_read_b128 %4, %9\n\tds_read_b128 %5, %9 offset:2048\n\tds_read_b128 %6, %9 offset:4096\n\tds_read_b128 %7, %9 offset:6144"
;                  : "=&v"(af[0]), "=&v"(af[1]), "=&v"(af[2]), "=&v"(af[3]), "=&v"(bfr[0]), "=&v"(bfr[1]), "=&v"(bfr[2]), "=&v"(bfr[3])
;                  : "v"(sa + a0), "v"(sa + b0) : "memory");
;     asm volatile("ds_read_b128 %0, %16\n\tds_read_b128 %1, %16 offset:2048\n\tds_read_b128 %2, %16 offset:4096\n\tds_read_b128 %3, %16 offset:6144\n\t"
;                  "ds_read_b128 %4, %17\n\tds_read_b128 %5, %17 offset:2048\n\tds_read_b128 %6, %17 offset:4096\n\tds_read_b128 %7, %17 offset:6144\n\t"
;                  "s_waitcnt lgkmcnt(8)"
;                  : "=&v"(ag[0]), "=&v"(ag[1]), "=&v"(ag[2]), "=&v"(ag[3]), "=&v"(bg[0]), "=&v"(bg[1]), "=&v"(bg[2]), "=&v"(bg[3]),
;                    "+v"(af[0]), "+v"(af[1]), "+v"(af[2]), "+v"(af[3]), "+v"(bfr[0]), "+v"(bfr[1]), "+v"(bfr[2]), "+v"(bfr[3])
;                  : "v"(sa + a1), "v"(sa + b1) : "memory");
; #pragma unroll
;     for (int mi = 0; mi < 4; ++mi)
; #pragma unroll
;       for (int ni = 0; ni < 4; ++ni) acc[mi][ni] = __builtin_amdgcn_mfma_f32_16x16x32_bf16(bfr[ni], af[mi], acc[mi][ni], 0, 0, 0);
;     asm volatile("s_waitcnt lgkmcnt(0)" : "+v"(ag[0]), "+v"(ag[1]), "+v"(ag[2]), "+v"(ag[3]), "+v"(bg[0]), "+v"(bg[1]), "+v"(bg[2]), "+v"(bg[3]) :: "memory");
; #pragma unroll
;     for (int mi = 0; mi < 4; ++mi)
; #pragma unroll
;       for (int ni = 0; ni < 4; ++ni) acc[mi][ni] = __builtin_amdgcn_mfma_f32_16x16x32_bf16(bg[ni], ag[mi], acc[mi][ni], 0, 0, 0);
;   }
.LBB0_69:
	s_add_i32 s20, s3, 0x8000
	s_and_b32 s3, s3, 0x8000
	s_and_b32 s21, s20, 0x8000
	v_add_u32_e32 v0, s3, v86
	v_or_b32_e32 v122, s3, v89
	s_waitcnt vmcnt(0)
	v_add_u32_e32 v154, s3, v87
	v_add_u32_e32 v155, s3, v88
	s_add_i32 s3, s1, s21
	s_waitcnt vmcnt(0)
	s_barrier
	v_lshl_add_u64 v[90:91], v[66:67], 0, s[22:23]
	s_add_i32 s21, s3, 0x4000
	s_mov_b32 m0, s3
	v_lshl_add_u64 v[92:93], v[68:69], 0, s[22:23]
	global_load_lds_dwordx4 v[90:91], off
	s_mov_b32 m0, s21
	v_lshl_add_u64 v[94:95], v[74:75], 0, s[22:23]
	global_load_lds_dwordx4 v[92:93], off
	s_add_i32 m0, s3, 0x400
	v_lshl_add_u64 v[96:97], v[76:77], 0, s[22:23]
	global_load_lds_dwordx4 v[94:95], off
	s_add_i32 m0, s3, 0x4400
	v_lshl_add_u64 v[98:99], v[78:79], 0, s[22:23]
	global_load_lds_dwordx4 v[96:97], off
	s_add_i32 m0, s3, 0x800
	v_lshl_add_u64 v[100:101], v[80:81], 0, s[22:23]
	global_load_lds_dwordx4 v[98:99], off
	s_add_i32 m0, s3, 0x4800
	v_lshl_add_u64 v[102:103], v[82:83], 0, s[22:23]
	global_load_lds_dwordx4 v[100:101], off
	s_add_i32 m0, s3, 0xc00
	v_lshl_add_u64 v[104:105], v[84:85], 0, s[22:23]
	global_load_lds_dwordx4 v[102:103], off
	s_add_i32 m0, s3, 0x4c00
	s_add_u32 s22, s22, 0x80
	global_load_lds_dwordx4 v[104:105], off
	s_addc_u32 s23, s23, 0
	v_mov_b32_e32 v214, v122
	ds_read_b128 v[90:93], v0
	ds_read_b128 v[106:109], v214
	ds_read_b128 v[110:113], v214 offset:2048
	ds_read_b128 v[114:117], v214 offset:4096
	ds_read_b128 v[118:121], v214 offset:6144
	ds_read_b128 v[94:97], v0 offset:2048
	ds_read_b128 v[98:101], v0 offset:4096
	ds_read_b128 v[102:105], v0 offset:6144
	ds_read_b128 v[122:125], v154
	ds_read_b128 v[138:141], v155
	ds_read_b128 v[142:145], v155 offset:2048
	ds_read_b128 v[146:149], v155 offset:4096
	ds_read_b128 v[150:153], v155 offset:6144
	ds_read_b128 v[126:129], v154 offset:2048
	ds_read_b128 v[130:133], v154 offset:4096
	ds_read_b128 v[134:137], v154 offset:6144
	s_cmpk_lg_i32 s22, 0x780
	s_waitcnt lgkmcnt(14)
	v_mfma_f32_16x16x32_bf16 v[62:65], v[106:109], v[90:93], v[62:65]
	s_waitcnt lgkmcnt(13)
	v_mfma_f32_16x16x32_bf16 v[58:61], v[110:113], v[90:93], v[58:61]
	s_waitcnt lgkmcnt(12)
	v_mfma_f32_16x16x32_bf16 v[54:57], v[114:117], v[90:93], v[54:57]
	s_waitcnt lgkmcnt(11)
	v_mfma_f32_16x16x32_bf16 v[46:49], v[118:121], v[90:93], v[46:49]
	s_waitcnt lgkmcnt(10)
	v_mfma_f32_16x16x32_bf16 v[42:45], v[106:109], v[94:97], v[42:45]
	v_mfma_f32_16x16x32_bf16 v[38:41], v[110:113], v[94:97], v[38:41]
	v_mfma_f32_16x16x32_bf16 v[34:37], v[114:117], v[94:97], v[34:37]
	v_mfma_f32_16x16x32_bf16 v[30:33], v[118:121], v[94:97], v[30:33]
	s_waitcnt lgkmcnt(9)
	v_mfma_f32_16x16x32_bf16 v[26:29], v[106:109], v[98:101], v[26:29]
	v_mfma_f32_16x16x32_bf16 v[22:25], v[110:113], v[98:101], v[22:25]
	v_mfma_f32_16x16x32_bf16 v[18:21], v[114:117], v[98:101], v[18:21]
	v_mfma_f32_16x16x32_bf16 v[14:17], v[118:121], v[98:101], v[14:17]
	s_waitcnt lgkmcnt(8)
	v_mfma_f32_16x16x32_bf16 v[10:13], v[106:109], v[102:105], v[10:13]
	v_mfma_f32_16x16x32_bf16 v[6:9], v[110:113], v[102:105], v[6:9]
	v_mfma_f32_16x16x32_bf16 v[2:5], v[114:117], v[102:105], v[2:5]
	v_mfma_f32_16x16x32_bf16 v[50:53], v[118:121], v[102:105], v[50:53]
	s_waitcnt lgkmcnt(6)
	v_mfma_f32_16x16x32_bf16 v[62:65], v[138:141], v[122:125], v[62:65]
	s_waitcnt lgkmcnt(5)
	v_mfma_f32_16x16x32_bf16 v[58:61], v[142:145], v[122:125], v[58:61]
	s_waitcnt lgkmcnt(4)
	v_mfma_f32_16x16x32_bf16 v[54:57], v[146:149], v[122:125], v[54:57]
	s_waitcnt lgkmcnt(3)
	v_mfma_f32_16x16x32_bf16 v[46:49], v[150:153], v[122:125], v[46:49]
	s_waitcnt lgkmcnt(2)
	v_mfma_f32_16x16x32_bf16 v[42:45], v[138:141], v[126:129], v[42:45]
	v_mfma_f32_16x16x32_bf16 v[38:41], v[142:145], v[126:129], v[38:41]
	v_mfma_f32_16x16x32_bf16 v[34:37], v[146:149], v[126:129], v[34:37]
	v_mfma_f32_16x16x32_bf16 v[30:33], v[150:153], v[126:129], v[30:33]
	s_waitcnt lgkmcnt(1)
	v_mfma_f32_16x16x32_bf16 v[26:29], v[138:141], v[130:133], v[26:29]
	v_mfma_f32_16x16x32_bf16 v[22:25], v[142:145], v[130:133], v[22:25]
	v_mfma_f32_16x16x32_bf16 v[18:21], v[146:149], v[130:133], v[18:21]
	v_mfma_f32_16x16x32_bf16 v[14:17], v[150:153], v[130:133], v[14:17]
	s_waitcnt lgkmcnt(0)
	v_mfma_f32_16x16x32_bf16 v[10:13], v[138:141], v[134:137], v[10:13]
	v_mfma_f32_16x16x32_bf16 v[6:9], v[142:145], v[134:137], v[6:9]
	v_mfma_f32_16x16x32_bf16 v[2:5], v[146:149], v[134:137], v[2:5]
	v_mfma_f32_16x16x32_bf16 v[50:53], v[150:153], v[134:137], v[50:53]
	s_mov_b32 s3, s20
	s_cbranch_scc1 .LBB0_69
; DI void gemm_dma(f32x4 (&acc)[4][4], const bf16_t* Ap, int lda, const bf16_t* Bp, int ldb, int K, char* lds) {
;     ...
;   for (int kt = 0; kt < nk; ++kt) {
;     asm volatile("s_waitcnt vmcnt(0)" ::: "memory");
;     __builtin_amdgcn_s_barrier();
;     asm volatile("" ::: "memory");
;     if (kt + 1 < nk) issue(kt + 1);
;     const unsigned sa = lbase + (unsigned)((kt & 1) * 32768);
;     bf16x8 af[4], bfr[4], ag[4], bg[4];
;     asm volatile("ds_read_b128 %0, %8\n\tds_read_b128 %1, %8 offset:2048\n\tds_read_b128 %2, %8 offset:4096\n\tds_read_b128 %3, %8 offset:6144\n\t"
;                  "ds_read_b128 %4, %9\n\tds_read_b128 %5, %9 offset:2048\n\tds_read_b128 %6, %9 offset:4096\n\tds_read_b128 %7, %9 offset:6144"
;                  : "=&v"(af[0]), "=&v"(af[1]), "=&v"(af[2]), "=&v"(af[3]), "=&v"(bfr[0]), "=&v"(bfr[1]), "=&v"(bfr[2]), "=&v"(bfr[3])
;                  : "v"(sa + a0), "v"(sa + b0) : "memory");
;     asm volatile("ds_read_b128 %0, %16\n\tds_read_b128 %1, %16 offset:2048\n\tds_read_b128 %2, %16 offset:4096\n\tds_read_b128 %3, %16 offset:6144\n\t"
;                  "ds_read_b128 %4, %17\n\tds_read_b128 %5, %17 offset:2048\n\tds_read_b128 %6, %17 offset:4096\n\tds_read_b128 %7, %17 offset:6144\n\t"
;                  "s_waitcnt lgkmcnt(8)"
;                  : "=&v"(ag[0]), "=&v"(ag[1]), "=&v"(ag[2]), "=&v"(ag[3]), "=&v"(bg[0]), "=&v"(bg[1]), "=&v"(bg[2]), "=&v"(bg[3]),
;                    "+v"(af[0]), "+v"(af[1]), "+v"(af[2]), "+v"(af[3]), "+v"(bfr[0]), "+v"(bfr[1]), "+v"(bfr[2]), "+v"(bfr[3])
;                  : "v"(sa + a1), "v"(sa + b1) : "memory");
; #pragma unroll
;     for (int mi = 0; mi < 4; ++mi)
; #pragma unroll
;       for (int ni = 0; ni < 4; ++ni) acc[mi][ni] = __builtin_amdgcn_mfma_f32_16x16x32_bf16(bfr[ni], af[mi], acc[mi][ni], 0, 0, 0);
;     asm volatile("s_waitcnt lgkmcnt(0)" : "+v"(ag[0]), "+v"(ag[1]), "+v"(ag[2]), "+v"(ag[3]), "+v"(bg[0]), "+v"(bg[1]), "+v"(bg[2]), "+v"(bg[3]) :: "memory");
; #pragma unroll
;     for (int mi = 0; mi < 4; ++mi)
; #pragma unroll
;       for (int ni = 0; ni < 4; ++ni) acc[mi][ni] = __builtin_amdgcn_mfma_f32_16x16x32_bf16(bg[ni], ag[mi], acc[mi][ni], 0, 0, 0);
;   }
; DI void phase_gemm_in(const Params& p, int l, char* lds) {
;     ...
;         const float rs = rsqrtf(p.ss1[mt * 128 + wm * 64 + mi * 16 + l15] * (1.0f / 1024.0f) + 1e-6f);
; #pragma unroll
	s_waitcnt vmcnt(0)
	s_barrier
	v_add_u32_e32 v0, 0x8000, v86
	v_or_b32_e32 v86, 0x8000, v89
	ds_read_b128 v[66:69], v0
	ds_read_b128 v[74:77], v0 offset:2048
	ds_read_b128 v[78:81], v0 offset:4096
	ds_read_b128 v[82:85], v0 offset:6144
	ds_read_b128 v[90:93], v86
	ds_read_b128 v[94:97], v86 offset:2048
	ds_read_b128 v[98:101], v86 offset:4096
	ds_read_b128 v[102:105], v86 offset:6144
	v_add_u32_e32 v0, 0x8000, v87
	v_add_u32_e32 v134, 0x8000, v88
	ds_read_b128 v[86:89], v0
	ds_read_b128 v[106:109], v0 offset:2048
	ds_read_b128 v[110:113], v0 offset:4096
	ds_read_b128 v[114:117], v0 offset:6144
	ds_read_b128 v[118:121], v134
	ds_read_b128 v[122:125], v134 offset:2048
	ds_read_b128 v[126:129], v134 offset:4096
	ds_read_b128 v[130:133], v134 offset:6144
	s_waitcnt lgkmcnt(8)
	s_lshl_b32 s46, s2, 7
	v_mfma_f32_16x16x32_bf16 v[62:65], v[90:93], v[66:69], v[62:65]
	s_waitcnt lgkmcnt(0)
	v_readlane_b32 s20, v254, 52
	v_readlane_b32 s21, v254, 53
	v_mfma_f32_16x16x32_bf16 v[46:49], v[102:105], v[66:69], v[46:49]
	s_barrier
	v_mfma_f32_16x16x32_bf16 v[42:45], v[90:93], v[74:77], v[42:45]
	v_readlane_b32 s22, v254, 54
	v_readlane_b32 s23, v254, 55
	v_readlane_b32 s24, v254, 56
	v_mfma_f32_16x16x32_bf16 v[38:41], v[94:97], v[74:77], v[38:41]
	v_readlane_b32 s25, v254, 57
	v_readlane_b32 s26, v254, 58
	v_readlane_b32 s27, v254, 59
	v_mfma_f32_16x16x32_bf16 v[34:37], v[98:101], v[74:77], v[34:37]
	s_cmp_gt_i32 s0, 12
	s_mov_b64 s[2:3], 0
	s_cselect_b64 s[30:31], -1, 0
	v_mfma_f32_16x16x32_bf16 v[30:33], v[102:105], v[74:77], v[30:33]
	s_cmp_lt_i32 s0, 13
	s_mov_b64 s[26:27], 0
	s_mov_b64 s[24:25], 0
	v_mfma_f32_16x16x32_bf16 v[26:29], v[90:93], v[78:81], v[26:29]
	s_mov_b64 s[22:23], 0
	v_mfma_f32_16x16x32_bf16 v[18:21], v[98:101], v[78:81], v[18:21]
	v_mfma_f32_16x16x32_bf16 v[14:17], v[102:105], v[78:81], v[14:17]
	v_mfma_f32_16x16x32_bf16 v[134:137], v[98:101], v[66:69], v[54:57]
	v_mfma_f32_16x16x32_bf16 v[54:57], v[118:121], v[86:89], v[62:65]
	v_mfma_f32_16x16x32_bf16 v[62:65], v[130:133], v[86:89], v[46:49]
	v_mfma_f32_16x16x32_bf16 v[46:49], v[118:121], v[106:109], v[42:45]
	v_mfma_f32_16x16x32_bf16 v[42:45], v[122:125], v[106:109], v[38:41]
	v_mfma_f32_16x16x32_bf16 v[38:41], v[126:129], v[106:109], v[34:37]
	v_mfma_f32_16x16x32_bf16 v[34:37], v[130:133], v[106:109], v[30:33]
	v_mfma_f32_16x16x32_bf16 v[30:33], v[118:121], v[110:113], v[26:29]
	v_mfma_f32_16x16x32_bf16 v[26:29], v[126:129], v[110:113], v[18:21]
	v_mfma_f32_16x16x32_bf16 v[18:21], v[130:133], v[110:113], v[14:17]
	s_nop 2
	v_add_u32_e32 v14, s46, v71
	v_ashrrev_i32_e32 v15, 31, v14
	v_lshl_add_u64 v[74:75], v[14:15], 2, s[20:21]
	v_mfma_f32_16x16x32_bf16 v[58:61], v[94:97], v[66:69], v[58:61]
	v_mfma_f32_16x16x32_bf16 v[66:69], v[102:105], v[82:85], v[50:53]
	v_mov_b32_e32 v0, v222
	v_mov_b32_e32 v105, v223
	v_mov_b32_e32 v104, v224
	v_mov_b32_e32 v102, v225
	v_mfma_f32_16x16x32_bf16 v[22:25], v[94:97], v[78:81], v[22:25]
	v_mfma_f32_16x16x32_bf16 v[10:13], v[90:93], v[82:85], v[10:13]
	v_mfma_f32_16x16x32_bf16 v[6:9], v[94:97], v[82:85], v[6:9]
	v_mfma_f32_16x16x32_bf16 v[2:5], v[98:101], v[82:85], v[2:5]
	v_mfma_f32_16x16x32_bf16 v[50:53], v[122:125], v[86:89], v[58:61]
	v_mfma_f32_16x16x32_bf16 v[58:61], v[126:129], v[86:89], v[134:137]
	v_mfma_f32_16x16x32_bf16 v[22:25], v[122:125], v[110:113], v[22:25]
	v_mfma_f32_16x16x32_bf16 v[14:17], v[118:121], v[114:117], v[10:13]
	v_mfma_f32_16x16x32_bf16 v[10:13], v[122:125], v[114:117], v[6:9]
	v_mfma_f32_16x16x32_bf16 v[6:9], v[126:129], v[114:117], v[2:5]
	v_mfma_f32_16x16x32_bf16 v[2:5], v[130:133], v[114:117], v[66:69]
	s_cbranch_scc1 .LBB0_77
	s_cmp_lt_u32 s0, 17
	s_cbranch_scc1 .LBB0_75
	s_cmp_lt_u32 s0, 21
	s_cbranch_scc1 .LBB0_76
	s_mov_b64 s[22:23], -1
	s_cmp_lt_u32 s0, 25
	s_cbranch_scc1 .LBB0_77
	s_sub_i32 s1, s0, 29
	s_cmp_lt_u32 s1, 4
	s_cselect_b64 s[2:3], -1, 0
	s_cmp_gt_u32 s0, 32
	s_mov_b64 s[22:23], 0
	s_cselect_b64 s[26:27], -1, 0
	s_branch .LBB0_77
